# dn_pre: next unit's K/V tile loads issued right after the current unit's fill (was loaded at unit start with an exposed wait)
# speedup vs baseline: 1.0040x; 1.0040x over previous
.LBB0_397:
	s_waitcnt vmcnt(0)
	v_mov_b32_e32 v0, v168
	s_lshl_b32 s51, s40, 2
	s_and_b32 s52, s40, 1
	v_readfirstlane_b32 s53, v0
	s_bfe_u32 s50, s40, 0x30001
	s_andn2_b32 s51, s51, 63
	v_ashrrev_i32_e32 v44, 2, v0
	s_cmp_eq_u32 s52, 0
	s_cselect_b64 s[36:37], -1, 0
	v_sub_u32_e32 v45, 63, v44
	v_cndmask_b32_e64 v45, v45, v44, s[36:37]
	v_add_u32_e32 v46, s51, v45
	v_ashrrev_i32_e32 v47, 31, v46
	v_readlane_b32 s2, v253, 7
	v_lshlrev_b64 v[46:47], 10, v[46:47]
	v_readlane_b32 s3, v253, 8
	v_lshlrev_b32_e32 v48, 4, v0
	s_lshl_b32 s30, s50, 7
	v_lshl_add_u64 v[50:51], s[2:3], 0, v[46:47]
	v_readlane_b32 s2, v252, 51
	v_readlane_b32 s3, v252, 52
	v_and_b32_e32 v48, 48, v48
	v_lshl_add_u64 v[50:51], v[50:51], 0, s[30:31]
	v_lshl_add_u64 v[46:47], s[2:3], 0, v[46:47]
	v_lshlrev_b32_e32 v48, 1, v48
	v_mov_b32_e32 v49, v2
	v_lshl_add_u64 v[46:47], v[46:47], 0, s[30:31]
	v_lshl_add_u64 v[50:51], v[50:51], 0, v[48:49]
	v_lshl_add_u64 v[46:47], v[46:47], 0, v[48:49]
	s_cmp_ge_u32 s40, s96
	s_cbranch_scc1 .Lmy_dn_noload
	global_load_dwordx4 v[60:63], v[50:51], off offset:16
	global_load_dwordx4 v[64:67], v[50:51], off
	global_load_dwordx4 v[68:71], v[46:47], off offset:16
	global_load_dwordx4 v[72:75], v[46:47], off
.Lmy_dn_noload:
	v_cmp_gt_i32_e32 vcc, 64, v0
	s_waitcnt lgkmcnt(0)
	s_barrier
	s_and_saveexec_b64 s[42:43], vcc
	s_cbranch_execz .LBB0_403
	s_cmp_eq_u32 s52, 0
	s_cselect_b64 s[36:37], -1, 0
	v_sub_u32_e32 v1, 63, v0
	v_cndmask_b32_e64 v1, v1, v0, s[36:37]
	v_add_u32_e32 v4, s51, v1
	v_ashrrev_i32_e32 v5, 31, v4
	v_readlane_b32 s18, v253, 15
	v_lshlrev_b64 v[4:5], 7, v[4:5]
	v_readlane_b32 s19, v253, 16
	s_lshl_b32 s2, s52, 3
	s_lshl_b32 s30, s52, 5
	v_lshl_add_u64 v[4:5], s[18:19], 0, v[4:5]
	v_readlane_b32 s18, v255, 3
	s_or_b32 s2, s2, s18
	s_or_b32 s20, s2, s50
	s_ashr_i32 s21, s20, 31
	v_readlane_b32 s80, v250, 17
	v_lshl_add_u64 v[4:5], v[4:5], 0, s[30:31]
	s_lshl_b32 s30, s50, 2
	s_lshl_b64 s[44:45], s[20:21], 2
	v_readlane_b32 s94, v250, 31
	v_readlane_b32 s95, v250, 32
	s_add_u32 s20, s94, s44
	v_lshl_add_u64 v[4:5], v[4:5], 0, s[30:31]
	s_addc_u32 s21, s95, s45
	global_load_dword v1, v[4:5], off
	global_load_dword v3, v[4:5], off offset:64
	s_mov_b32 s2, 0x41700000
	global_load_dword v4, v2, s[20:21]
	s_add_u32 s46, s92, s44
	s_addc_u32 s47, s93, s45
	global_load_dword v76, v2, s[46:47]
	v_readlane_b32 s19, v255, 4
	v_readlane_b32 s81, v250, 18
	v_readlane_b32 s82, v250, 19
	v_readlane_b32 s83, v250, 20
	v_readlane_b32 s84, v250, 21
	v_readlane_b32 s85, v250, 22
	v_readlane_b32 s86, v250, 23
	v_readlane_b32 s87, v250, 24
	v_readlane_b32 s88, v250, 25
	v_readlane_b32 s89, v250, 26
	v_readlane_b32 s90, v250, 27
	v_readlane_b32 s91, v250, 28
	v_readlane_b32 s92, v250, 29
	v_readlane_b32 s93, v250, 30
	s_waitcnt vmcnt(0)
	v_add_f32_e32 v1, v1, v4
	v_cmp_nlt_f32_e64 s[36:37], s2, v1
	s_and_saveexec_b64 s[46:47], s[36:37]
	s_cbranch_execz .LBB0_402
	v_mul_f32_e32 v4, 0x3fb8aa3b, v1
	v_exp_f32_e32 v4, v4
	s_mov_b32 s2, 0xc1200000
	v_cmp_ngt_f32_e64 s[36:37], s2, v1
	s_and_saveexec_b64 s[48:49], s[36:37]
	s_cbranch_execz .LBB0_401
	v_add_f32_e32 v1, 1.0, v4
	s_mov_b32 s2, 0x800000
	v_cmp_gt_f32_e64 s[36:37], s2, v1
	s_mov_b32 s2, 0x3f317217
	s_mov_b32 s1, 0x7f800000
	v_cndmask_b32_e64 v4, 0, 32, s[36:37]
	v_ldexp_f32 v1, v1, v4
	v_log_f32_e32 v1, v1
	s_nop 0
	v_mul_f32_e32 v4, 0x3f317217, v1
	v_fma_f32 v4, v1, s2, -v4
	v_fmac_f32_e32 v4, 0x3377d1cf, v1
	v_fmac_f32_e32 v4, 0x3f317217, v1
	v_cmp_lt_f32_e64 s[38:39], |v1|, s1
	s_nop 1
	v_cndmask_b32_e64 v1, v1, v4, s[38:39]
	v_cndmask_b32_e64 v4, 0, v173, s[36:37]
	v_sub_f32_e32 v4, v1, v4

.LBB0_403:
	s_or_b64 exec, exec, s[42:43]
	s_ashr_i32 s41, s53, 6
	v_ashrrev_i32_e32 v23, 2, v0
	s_cmp_eq_u32 s52, 0
	s_cselect_b64 s[36:37], -1, 0
	v_sub_u32_e32 v4, 63, v23
	v_cndmask_b32_e64 v4, v4, v23, s[36:37]
	v_add_u32_e32 v4, s51, v4
	v_ashrrev_i32_e32 v5, 31, v4
	v_readlane_b32 s2, v253, 7
	v_lshlrev_b64 v[4:5], 10, v[4:5]
	v_readlane_b32 s3, v253, 8
	v_lshlrev_b32_e32 v30, 4, v0
	s_lshl_b32 s30, s50, 7
	v_lshl_add_u64 v[6:7], s[2:3], 0, v[4:5]
	v_readlane_b32 s2, v252, 51
	v_readlane_b32 s3, v252, 52
	v_and_b32_e32 v24, 48, v30
	v_lshl_add_u64 v[6:7], v[6:7], 0, s[30:31]
	v_lshl_add_u64 v[4:5], s[2:3], 0, v[4:5]
	v_lshlrev_b32_e32 v20, 1, v24
	v_mov_b32_e32 v21, v2
	v_lshl_add_u64 v[4:5], v[4:5], 0, s[30:31]
	v_lshl_add_u64 v[8:9], v[6:7], 0, v[20:21]
	v_lshl_add_u64 v[16:17], v[4:5], 0, v[20:21]
	s_waitcnt lgkmcnt(0)
	s_barrier
	s_waitcnt vmcnt(0)
	v_mov_b32_e32 v4, v60
	v_mov_b32_e32 v5, v61
	v_mov_b32_e32 v6, v62
	v_mov_b32_e32 v7, v63
	v_mov_b32_e32 v8, v64
	v_mov_b32_e32 v9, v65
	v_mov_b32_e32 v10, v66
	v_mov_b32_e32 v11, v67
	v_mov_b32_e32 v12, v68
	v_mov_b32_e32 v13, v69
	v_mov_b32_e32 v14, v70
	v_mov_b32_e32 v15, v71
	v_mov_b32_e32 v16, v72
	v_mov_b32_e32 v17, v73
	v_mov_b32_e32 v18, v74
	v_mov_b32_e32 v19, v75
	s_add_i32 s20, s40, s96
	s_cmpk_gt_i32 s20, 0xbff
	s_cbranch_scc1 .Lmy_dn_nopf
	s_lshl_b32 s20, s96, 12
	s_mov_b32 s21, 0
	v_lshl_add_u64 v[50:51], v[50:51], 0, s[20:21]
	v_lshl_add_u64 v[46:47], v[46:47], 0, s[20:21]
	global_load_dwordx4 v[60:63], v[50:51], off offset:16
	global_load_dwordx4 v[64:67], v[50:51], off
	global_load_dwordx4 v[68:71], v[46:47], off offset:16
	global_load_dwordx4 v[72:75], v[46:47], off
.Lmy_dn_nopf:
	s_movk_i32 s1, 0x90
	v_mul_lo_u32 v22, v23, s1
	v_add_u32_e32 v20, v22, v20
	s_movk_i32 s2, 0xff74
	v_bfe_u32 v1, v0, 4, 2
	v_and_b32_e32 v3, 15, v0
	s_cmp_gt_i32 s41, 9
	v_lshlrev_b32_e32 v31, 2, v1
	ds_write_b128 v20, v[8:11] offset:55808
	ds_write_b128 v20, v[4:7] offset:55824
	v_mad_u64_u32 v[20:21], s[20:21], v23, s2, v[22:23]
	ds_read2st64_b32 v[20:21], v20 offset0:216 offset1:217
	v_lshlrev_b32_e32 v22, 16, v16
	s_waitcnt lgkmcnt(0)
	v_mul_f32_e32 v20, 0x3fb8aa3b, v20
	v_exp_f32_e32 v20, v20
	v_mov_b32_e32 v32, v21
	v_mul_f32_e32 v28, v21, v20
	v_mul_lo_u32 v20, v23, s33
	v_and_b32_e32 v23, 0xffff0000, v16
	v_lshl_add_u32 v29, v24, 2, v20
	v_pk_mul_f32 v[20:21], v[32:33], v[22:23] op_sel_hi:[0,1]
	v_lshlrev_b32_e32 v22, 16, v8
	v_and_b32_e32 v23, 0xffff0000, v8
	v_lshlrev_b32_e32 v8, 16, v9
	v_and_b32_e32 v9, 0xffff0000, v9
	v_lshlrev_b32_e32 v16, 16, v17
	v_and_b32_e32 v17, 0xffff0000, v17
	v_pk_mul_f32 v[26:27], v[28:29], v[8:9] op_sel_hi:[0,1]
	v_lshlrev_b32_e32 v8, 16, v18
	v_and_b32_e32 v9, 0xffff0000, v18
	v_pk_mul_f32 v[24:25], v[28:29], v[22:23] op_sel_hi:[0,1]
	v_pk_mul_f32 v[22:23], v[32:33], v[16:17] op_sel_hi:[0,1]
	v_pk_mul_f32 v[16:17], v[32:33], v[8:9] op_sel_hi:[0,1]
	v_lshlrev_b32_e32 v8, 16, v10
	v_and_b32_e32 v9, 0xffff0000, v10
	v_lshlrev_b32_e32 v10, 16, v11
	v_and_b32_e32 v11, 0xffff0000, v11
	v_pk_mul_f32 v[8:9], v[28:29], v[8:9] op_sel_hi:[0,1]
	v_lshlrev_b32_e32 v18, 16, v19
	v_and_b32_e32 v19, 0xffff0000, v19
	v_pk_mul_f32 v[10:11], v[28:29], v[10:11] op_sel_hi:[0,1]
	v_pk_mul_f32 v[18:19], v[32:33], v[18:19] op_sel_hi:[0,1]
	ds_write_b128 v29, v[8:11] offset:272
	v_lshlrev_b32_e32 v10, 16, v4
	v_and_b32_e32 v11, 0xffff0000, v4
	ds_write_b128 v29, v[16:19] offset:16
	v_lshlrev_b32_e32 v8, 16, v12
	v_and_b32_e32 v9, 0xffff0000, v12
	v_pk_mul_f32 v[16:17], v[28:29], v[10:11] op_sel_hi:[0,1]
	v_lshlrev_b32_e32 v10, 16, v13
	v_and_b32_e32 v11, 0xffff0000, v13
	v_lshlrev_b32_e32 v4, 16, v5
	v_and_b32_e32 v5, 0xffff0000, v5
	v_pk_mul_f32 v[8:9], v[32:33], v[8:9] op_sel_hi:[0,1]
	v_pk_mul_f32 v[10:11], v[32:33], v[10:11] op_sel_hi:[0,1]
	v_pk_mul_f32 v[18:19], v[28:29], v[4:5] op_sel_hi:[0,1]
	v_lshlrev_b32_e32 v4, 16, v14
	v_and_b32_e32 v5, 0xffff0000, v14
	ds_write_b128 v29, v[8:11] offset:32
	v_pk_mul_f32 v[8:9], v[32:33], v[4:5] op_sel_hi:[0,1]
	v_lshlrev_b32_e32 v4, 16, v6
	v_and_b32_e32 v5, 0xffff0000, v6
	v_lshlrev_b32_e32 v10, 16, v15
	v_and_b32_e32 v11, 0xffff0000, v15
	v_lshlrev_b32_e32 v6, 16, v7
	v_and_b32_e32 v7, 0xffff0000, v7
	v_pk_mul_f32 v[4:5], v[28:29], v[4:5] op_sel_hi:[0,1]
	v_pk_mul_f32 v[10:11], v[32:33], v[10:11] op_sel_hi:[0,1]
	v_pk_mul_f32 v[6:7], v[28:29], v[6:7] op_sel_hi:[0,1]
	ds_write_b128 v29, v[20:23]
	ds_write_b128 v29, v[24:27] offset:256
	ds_write_b128 v29, v[16:19] offset:288
	ds_write_b128 v29, v[8:11] offset:48
	ds_write_b128 v29, v[4:7] offset:304
	s_waitcnt lgkmcnt(0)
	s_barrier
	s_cbranch_scc1 .LBB0_417
	v_lshlrev_b32_e32 v8, 4, v1
	s_mov_b32 s20, s41
	s_branch .LBB0_406
